# v5 + NA: next key-row K/V global loads issued before the publish barrier (more load lead per row)
# speedup vs baseline: 1.0001x; 1.0001x over previous
.LBB0_464:
	s_add_i32 s72, s55, 1
	s_cmp_ge_u32 s72, s79
	s_cselect_b64 s[4:5], -1, 0
	s_and_b64 vcc, exec, s[4:5]
	s_waitcnt lgkmcnt(0)
	s_barrier
	s_waitcnt vmcnt(0)
	ds_write_b128 v202, v[146:149]
	ds_write_b128 v203, v[154:157]
	ds_write_b128 v204, v[150:153] offset:32768
	ds_write_b128 v205, v[158:161] offset:32768
	s_waitcnt lgkmcnt(0)
	s_cbranch_vccnz .LBB0_466
	v_add_co_u32_e32 v4, vcc, 0xffffc000, v164
	s_nop 1
	v_addc_co_u32_e32 v5, vcc, -1, v165, vcc
	v_add_co_u32_e32 v6, vcc, 0xf7ffc000, v164
	s_nop 1
	v_addc_co_u32_e32 v7, vcc, -1, v165, vcc
	global_load_dwordx4 v[146:149], v[4:5], off
	global_load_dwordx4 v[150:153], v[6:7], off
	v_add_co_u32_e32 v4, vcc, 0xf8000000, v164
	s_nop 1
	v_addc_co_u32_e32 v5, vcc, -1, v165, vcc
	global_load_dwordx4 v[154:157], v[164:165], off
	global_load_dwordx4 v[158:161], v[4:5], off
.LBB0_466:
	s_barrier
	s_cmp_ge_u32 s55, s82
	s_cselect_b64 s[6:7], -1, 0
	s_cmp_lt_u32 s55, s83
	s_cselect_b64 s[54:55], -1, 0
	s_and_b64 s[6:7], s[6:7], s[54:55]
	s_andn2_b64 vcc, exec, s[6:7]
	s_cbranch_vccnz .LBB0_472
	v_add_u32_e32 v2, s60, v200
	v_add_u32_e32 v4, s60, v199
	v_add_u32_e32 v5, s60, v198
	v_add_u32_e32 v6, s60, v197
	v_add_u32_e32 v7, s60, v196
	v_add_u32_e32 v8, s60, v195
	v_add_u32_e32 v9, s60, v194
	v_add_u32_e32 v10, s60, v193
	ds_read_b32 v2, v2
	ds_read_b32 v16, v4
	ds_read_b32 v17, v5
	ds_read_b32 v210, v6
	ds_read_b32 v211, v7
	ds_read_b32 v215, v8
	ds_read_b32 v232, v9
	ds_read_b32 v233, v10
	v_add_u32_e32 v4, s60, v192
	v_add_u32_e32 v5, s60, v191
	v_add_u32_e32 v6, s60, v190
	v_add_u32_e32 v7, s60, v189
	v_add_u32_e32 v8, s60, v188
	v_add_u32_e32 v9, s60, v187
	v_add_u32_e32 v10, s60, v186
	v_add_u32_e32 v11, s60, v185
	ds_read_b32 v234, v4
	ds_read_b32 v235, v5
	ds_read_b32 v236, v6
	ds_read_b32 v237, v7
	ds_read_b32 v238, v8
	ds_read_b32 v239, v9
	ds_read_b32 v240, v10
	ds_read_b32 v241, v11
	v_add_u32_e32 v4, s60, v184
	v_add_u32_e32 v5, s60, v183
	v_add_u32_e32 v6, s60, v182
	v_add_u32_e32 v7, s60, v181
	ds_read_b32 v242, v4
	ds_read_b32 v251, v5
	ds_read_b32 v252, v6
	ds_read_b32 v253, v7
	v_add_u32_e32 v4, v169, v173
	v_add_u32_e32 v8, v170, v173
	v_add_u32_e32 v12, v169, v174
	v_add_u32_e32 v82, v170, v174
	ds_read_b128 v[4:7], v4 offset:32768
	ds_read_b128 v[8:11], v8 offset:32768
	ds_read_b128 v[12:15], v12 offset:32768
	ds_read_b128 v[206:209], v82 offset:32768
	v_add_u32_e32 v82, v169, v175
	v_add_u32_e32 v83, v170, v175
	ds_read_b128 v[216:219], v82 offset:32768
	ds_read_b128 v[220:223], v83 offset:32768
	v_add_u32_e32 v82, v169, v176
	v_add_u32_e32 v83, v170, v176
	ds_read_b128 v[224:227], v82 offset:32768
	ds_read_b128 v[228:231], v83 offset:32768
	s_waitcnt lgkmcnt(7)
	v_mfma_f32_32x32x16_bf16 v[82:97], v[4:7], v[138:141], 0
	s_waitcnt lgkmcnt(6)
	v_mfma_f32_32x32x16_bf16 v[98:113], v[8:11], v[138:141], 0
	s_waitcnt lgkmcnt(5)
	v_mfma_f32_32x32x16_bf16 v[82:97], v[12:15], v[114:117], v[82:97]
	s_waitcnt lgkmcnt(4)
	v_mfma_f32_32x32x16_bf16 v[98:113], v[206:209], v[114:117], v[98:113]
	s_waitcnt lgkmcnt(3)
	v_mfma_f32_32x32x16_bf16 v[82:97], v[216:219], v[118:121], v[82:97]
	s_waitcnt lgkmcnt(2)
	v_mfma_f32_32x32x16_bf16 v[98:113], v[220:223], v[118:121], v[98:113]
	s_waitcnt lgkmcnt(1)
	v_mfma_f32_32x32x16_bf16 v[82:97], v[224:227], v[122:125], v[82:97]
	s_waitcnt lgkmcnt(0)
	v_mfma_f32_32x32x16_bf16 v[98:113], v[228:231], v[122:125], v[98:113]
	v_add_u32_e32 v4, v169, v177
	v_add_u32_e32 v8, v170, v177
	v_add_u32_e32 v12, v169, v178
	v_add_u32_e32 v206, v170, v178
	v_add_u32_e32 v216, v169, v179
	v_add_u32_e32 v220, v170, v179
	v_add_u32_e32 v224, v169, v180
	v_add_u32_e32 v228, v170, v180
	ds_read_b128 v[4:7], v4 offset:32768
	ds_read_b128 v[8:11], v8 offset:32768
	ds_read_b128 v[12:15], v12 offset:32768
	ds_read_b128 v[206:209], v206 offset:32768
	ds_read_b128 v[216:219], v216 offset:32768
	ds_read_b128 v[220:223], v220 offset:32768
	ds_read_b128 v[224:227], v224 offset:32768
	ds_read_b128 v[228:231], v228 offset:32768
	s_waitcnt lgkmcnt(7)
	v_mfma_f32_32x32x16_bf16 v[82:97], v[4:7], v[126:129], v[82:97]
	s_waitcnt lgkmcnt(6)
	v_mfma_f32_32x32x16_bf16 v[98:113], v[8:11], v[126:129], v[98:113]
	s_waitcnt lgkmcnt(5)
	v_mfma_f32_32x32x16_bf16 v[82:97], v[12:15], v[130:133], v[82:97]
	s_waitcnt lgkmcnt(4)
	v_mfma_f32_32x32x16_bf16 v[98:113], v[206:209], v[130:133], v[98:113]
	s_waitcnt lgkmcnt(3)
	v_mfma_f32_32x32x16_bf16 v[82:97], v[216:219], v[134:137], v[82:97]
	s_waitcnt lgkmcnt(2)
	v_mfma_f32_32x32x16_bf16 v[98:113], v[220:223], v[134:137], v[98:113]
	s_waitcnt lgkmcnt(1)
	v_mfma_f32_32x32x16_bf16 v[82:97], v[224:227], v[142:145], v[82:97]
	s_waitcnt lgkmcnt(0)
	v_mfma_f32_32x32x16_bf16 v[98:113], v[228:231], v[142:145], v[98:113]
	s_nop 9
	v_fmac_f32_e32 v2, 0x3e0293ee, v82
	s_nop 0
	v_fmac_f32_e32 v242, 0x3e0293ee, v98
	v_cndmask_b32_e64 v2, v246, v2, s[12:13]
	v_cndmask_b32_e64 v98, v246, v242, s[14:15]
	v_fmac_f32_e32 v16, 0x3e0293ee, v83
	v_fmac_f32_e32 v251, 0x3e0293ee, v99
	s_mov_b32 s6, 0xff800000
	v_cndmask_b32_e64 v5, v246, v16, s[16:17]
	v_cndmask_b32_e64 v99, v246, v251, s[18:19]
	v_fmac_f32_e32 v17, 0x3e0293ee, v84
	v_fmac_f32_e32 v252, 0x3e0293ee, v100
	v_max3_f32 v4, v2, s6, v98
	v_cndmask_b32_e64 v6, v246, v17, s[20:21]
	v_cndmask_b32_e64 v100, v246, v252, s[22:23]
	v_fmac_f32_e32 v210, 0x3e0293ee, v85
	v_fmac_f32_e32 v253, 0x3e0293ee, v101
	v_max3_f32 v4, v4, v5, v99
	v_cndmask_b32_e64 v7, v246, v210, s[24:25]
	v_cndmask_b32_e64 v101, v246, v253, s[26:27]
	v_fmac_f32_e32 v211, 0x3e0293ee, v86
	v_fmac_f32_e32 v215, 0x3e0293ee, v87
	v_max3_f32 v4, v4, v6, v100
	v_cndmask_b32_e64 v8, v246, v211, s[28:29]
	v_cndmask_b32_e64 v9, v246, v215, s[30:31]
	v_fmac_f32_e32 v232, 0x3e0293ee, v88
	v_fmac_f32_e32 v233, 0x3e0293ee, v89
	v_max3_f32 v4, v4, v7, v101
	v_cndmask_b32_e64 v10, v246, v232, s[34:35]
	v_cndmask_b32_e64 v11, v246, v233, s[36:37]
	v_fmac_f32_e32 v234, 0x3e0293ee, v90
	v_fmac_f32_e32 v235, 0x3e0293ee, v91
	v_max3_f32 v4, v4, v8, v9
	v_cndmask_b32_e64 v13, v246, v234, s[38:39]
	v_cndmask_b32_e64 v14, v246, v235, s[40:41]
	v_fmac_f32_e32 v236, 0x3e0293ee, v92
	v_fmac_f32_e32 v237, 0x3e0293ee, v93
	v_max3_f32 v4, v4, v10, v11
	v_cndmask_b32_e64 v15, v246, v236, s[42:43]
	v_cndmask_b32_e64 v16, v246, v237, s[44:45]
	v_fmac_f32_e32 v238, 0x3e0293ee, v94
	v_fmac_f32_e32 v239, 0x3e0293ee, v95
	v_max3_f32 v4, v4, v13, v14
	v_cndmask_b32_e64 v17, v246, v238, s[46:47]
	v_cndmask_b32_e64 v82, v246, v239, s[48:49]
	v_fmac_f32_e32 v240, 0x3e0293ee, v96
	v_max3_f32 v4, v4, v15, v16
	v_fmac_f32_e32 v241, 0x3e0293ee, v97
	v_cndmask_b32_e64 v83, v246, v240, s[50:51]
	v_max3_f32 v4, v4, v17, v82
	v_cndmask_b32_e64 v84, v246, v241, s[52:53]
	v_max3_f32 v4, v4, v83, v84
	v_mov_b32_e32 v12, v4
	s_nop 1
	v_permlane32_swap_b32_e32 v4, v12
	v_max_f32_e32 v12, v12, v12
	v_max_f32_e32 v4, v4, v4
	v_max_f32_e32 v4, v4, v12
	v_sub_f32_e32 v12, v4, v201
	s_mov_b32 s6, 0x41000000
	v_cmp_lt_f32_e32 vcc, s6, v12
	s_cmp_eq_u64 vcc, 0
	v_max_f32_e32 v12, v201, v201
	v_max_f32_e32 v12, v12, v4
	s_cselect_b64 s[54:55], -1, 0
	v_sub_f32_e32 v4, v201, v12
	v_cndmask_b32_e64 v201, v12, v201, s[54:55]
	v_sub_f32_e32 v2, v2, v201
	v_exp_f32_e32 v2, v2
	v_sub_f32_e32 v5, v5, v201
	v_exp_f32_e32 v5, v5
	v_sub_f32_e32 v6, v6, v201
	v_exp_f32_e32 v6, v6
	v_sub_f32_e32 v7, v7, v201
	v_exp_f32_e32 v7, v7
	v_sub_f32_e32 v8, v8, v201
	v_add_f32_e32 v12, 0, v2
	v_exp_f32_e32 v8, v8
	v_sub_f32_e32 v9, v9, v201
	v_add_f32_e32 v12, v5, v12
	v_exp_f32_e32 v9, v9
	v_sub_f32_e32 v10, v10, v201
	v_add_f32_e32 v12, v6, v12
	v_exp_f32_e32 v10, v10
	v_sub_f32_e32 v11, v11, v201
	v_add_f32_e32 v85, v7, v12
	v_exp_f32_e32 v12, v11
	v_add_f32_e32 v11, v8, v85
	v_add_f32_e32 v11, v9, v11
	v_add_f32_e32 v11, v10, v11
	v_add_f32_e32 v85, v12, v11
	v_sub_f32_e32 v11, v13, v201
	v_exp_f32_e32 v11, v11
	v_sub_f32_e32 v13, v14, v201
	v_exp_f32_e32 v13, v13
	v_sub_f32_e32 v14, v15, v201
	v_exp_f32_e32 v14, v14
	v_sub_f32_e32 v15, v16, v201
	v_exp_f32_e32 v15, v15
	v_add_f32_e32 v16, v11, v85
	v_add_f32_e32 v16, v13, v16
	v_add_f32_e32 v16, v14, v16
	v_add_f32_e32 v86, v15, v16
	v_sub_f32_e32 v16, v17, v201
	v_exp_f32_e32 v16, v16
	v_sub_f32_e32 v17, v82, v201
	v_exp_f32_e32 v17, v17
	v_sub_f32_e32 v82, v83, v201
	v_exp_f32_e32 v82, v82
	v_sub_f32_e32 v83, v84, v201
	v_exp_f32_e32 v85, v83
	v_add_f32_e32 v83, v16, v86
	v_add_f32_e32 v83, v17, v83
	v_add_f32_e32 v83, v82, v83
	v_add_f32_e32 v88, v85, v83
	v_sub_f32_e32 v83, v98, v201
	v_exp_f32_e32 v83, v83
	v_sub_f32_e32 v84, v99, v201
	v_exp_f32_e32 v84, v84
	v_sub_f32_e32 v86, v100, v201
	v_exp_f32_e32 v86, v86
	v_sub_f32_e32 v87, v101, v201
	v_exp_f32_e32 v87, v87
	v_add_f32_e32 v88, v83, v88
	v_add_f32_e32 v88, v84, v88
	v_exp_f32_e32 v4, v4
	v_add_f32_e32 v88, v86, v88
	v_add_f32_e32 v88, v87, v88
	v_mov_b32_e32 v89, v88
	s_nop 1
	v_permlane32_swap_b32_e32 v88, v89
	s_cbranch_vccz .LBB0_471
	s_and_saveexec_b64 s[6:7], s[8:9]
	ds_write_b32 v168, v4 offset:128
	s_or_b64 exec, exec, s[6:7]
	s_waitcnt lgkmcnt(0)
	v_add_u32_e32 v102, s78, v162
	ds_read_b128 v[90:93], v102 offset:224
	ds_read_b128 v[94:97], v102 offset:192
	ds_read_b128 v[98:101], v102 offset:160
	ds_read_b128 v[102:105], v102 offset:128
	s_waitcnt lgkmcnt(3)
	v_pk_mul_f32 v[78:79], v[78:79], v[90:91]
	s_waitcnt lgkmcnt(2)
	v_pk_mul_f32 v[74:75], v[74:75], v[94:95]
	s_waitcnt lgkmcnt(1)
	v_pk_mul_f32 v[70:71], v[70:71], v[98:99]
	v_pk_mul_f32 v[80:81], v[80:81], v[92:93]
	v_pk_mul_f32 v[76:77], v[76:77], v[96:97]
	v_pk_mul_f32 v[72:73], v[72:73], v[100:101]
	s_waitcnt lgkmcnt(0)
	v_pk_mul_f32 v[68:69], v[68:69], v[104:105]
	v_pk_mul_f32 v[66:67], v[66:67], v[102:103]
	v_pk_mul_f32 v[62:63], v[62:63], v[90:91]
	v_pk_mul_f32 v[58:59], v[58:59], v[94:95]
	v_pk_mul_f32 v[54:55], v[54:55], v[98:99]
	v_pk_mul_f32 v[64:65], v[64:65], v[92:93]
	v_pk_mul_f32 v[60:61], v[60:61], v[96:97]
	v_pk_mul_f32 v[56:57], v[56:57], v[100:101]
	v_pk_mul_f32 v[52:53], v[52:53], v[104:105]
	v_pk_mul_f32 v[50:51], v[50:51], v[102:103]
	v_pk_mul_f32 v[46:47], v[46:47], v[90:91]
	v_pk_mul_f32 v[42:43], v[42:43], v[94:95]
	v_pk_mul_f32 v[38:39], v[38:39], v[98:99]
	v_pk_mul_f32 v[48:49], v[48:49], v[92:93]
	v_pk_mul_f32 v[44:45], v[44:45], v[96:97]
	v_pk_mul_f32 v[40:41], v[40:41], v[100:101]
	v_pk_mul_f32 v[36:37], v[36:37], v[104:105]
	v_pk_mul_f32 v[34:35], v[34:35], v[102:103]
	v_pk_mul_f32 v[30:31], v[30:31], v[90:91]
	v_pk_mul_f32 v[26:27], v[26:27], v[94:95]
	v_pk_mul_f32 v[22:23], v[22:23], v[98:99]
	v_pk_mul_f32 v[32:33], v[32:33], v[92:93]
	v_pk_mul_f32 v[28:29], v[28:29], v[96:97]
	v_pk_mul_f32 v[24:25], v[24:25], v[100:101]
	v_pk_mul_f32 v[20:21], v[20:21], v[104:105]
	v_pk_mul_f32 v[18:19], v[18:19], v[102:103]
